# context-attention items moved to workgroups 64-127 (off the workgroups that own the third S5-out round)
# speedup vs baseline: 1.0095x; 1.0046x over previous
; DEV int vbsel() { return __builtin_amdgcn_readfirstlane((int)(threadIdx.x >> 8)); }
; DEV void ph_prep_early(const P& p, char* smem) {
;   const int skip = gridDim.x > 64 ? 32 : 0;
;   if ((int)blockIdx.x < skip) return;
;   const int vb0 = ((int)blockIdx.x - skip) * 2 + vbsel(), vg = ((int)gridDim.x - skip) * 2;
; DEV void ph_attn(const P& p, int l, bool need, char* smem) {
;     ...
;     attn_item(p, bh, qb * 256, 68, (bh >> 3) * 4096 + qb * 256, smem);
;   }
;   if (need) for (int it = blockIdx.x; it < 64; it += gridDim.x) attn_item(p, it, 4096, 4, MLAT + (it >> 3) * 256, smem);
.LBB0_34:
	s_or_b64 exec, exec, s[2:3]
	s_cmp_gt_u32 s54, 64
	s_cselect_b32 s3, 32, 0
	s_cmp_ge_i32 s73, s3
	s_cselect_b64 s[4:5], -1, 0
	v_writelane_b32 v253, s4, 3
	s_lshl_b32 s91, s54, 1
	s_mul_i32 s2, s55, s54
	v_writelane_b32 v253, s5, 4
	s_sub_i32 s4, s54, s3
	s_lshl_b32 s79, s4, 1
	s_sub_i32 s4, s73, s3
	s_lshl_b32 s4, s4, 1
	s_cmpk_lt_i32 s73, 0x400
	v_writelane_b32 v253, s4, 5
	s_cselect_b64 s[4:5], -1, 0
	v_writelane_b32 v253, s4, 6
	s_cmpk_ge_i32 s54, 0x80
	s_cselect_b32 s4, 64, 0
	s_sub_i32 s4, s73, s4
	s_cmp_lt_u32 s4, 64
	s_barrier
; DEV void ph_attn(const P& p, int l, bool need, char* smem) {
;     ...
;     attn_item(p, bh, qb * 256, 68, (bh >> 3) * 4096 + qb * 256, smem);
;   }
;   if (need) for (int it = blockIdx.x; it < 64; it += gridDim.x) attn_item(p, it, 4096, 4, MLAT + (it >> 3) * 256, smem);
	v_writelane_b32 v253, s5, 7
	s_cselect_b64 s[4:5], -1, 0
	v_writelane_b32 v253, s4, 8
	s_ashr_i32 s55, s73, 31
	s_nop 0
	v_writelane_b32 v253, s5, 9
	s_lshr_b32 s4, s55, 29
	s_add_i32 s4, s73, s4
	s_ashr_i32 s5, s4, 3
	s_and_b32 s4, s4, -8
	v_writelane_b32 v253, s5, 10
	s_sub_i32 s4, s73, s4
	v_writelane_b32 v253, s4, 11
	s_load_dword s4, s[88:89], 0x100
	s_ashr_i32 s51, s54, 31
	s_add_u32 s18, s0, 0x1e4cd200
	s_addc_u32 s19, s1, 0
	s_mov_b32 s28, 0x6dc9c883
	s_waitcnt lgkmcnt(0)
	s_mul_i32 s2, s2, s4
	s_add_u32 s4, s0, 0x1e4cd400
	v_writelane_b32 v253, s2, 12
	s_addc_u32 s5, s1, 0
	v_writelane_b32 v253, s4, 13
	s_mov_b32 s30, 0x54442d18
	v_mbcnt_lo_u32_b32 v0, -1, 0
	v_writelane_b32 v253, s5, 14
	s_add_u32 s4, s0, 0x1e4cd500
	s_addc_u32 s5, s1, 0
	v_writelane_b32 v253, s4, 15
	v_mov_b32_e32 v41, 0
	s_mov_b32 s29, 0x3fc45f30
	v_writelane_b32 v253, s5, 16
	s_add_u32 s4, s0, 0x1e4cd600
	s_addc_u32 s5, s1, 0
	v_writelane_b32 v253, s4, 17
	s_mov_b32 s31, 0xc01921fb
	v_mov_b32_e32 v200, 1
	v_writelane_b32 v253, s5, 18
	s_add_u32 s4, s0, 0x1e4cd700
	s_addc_u32 s5, s1, 0
	v_writelane_b32 v253, s4, 19
	v_mov_b32_e32 v236, 0x7f800000
	v_mbcnt_hi_u32_b32 v237, -1, v0
	v_writelane_b32 v253, s5, 20
	s_add_u32 s4, s0, 0x1e4cd800
	s_addc_u32 s5, s1, 0
	v_writelane_b32 v253, s4, 21
	v_mov_b32_e32 v240, 0x358637bd
	v_mov_b32_e32 v239, 0xcf
	v_writelane_b32 v253, s5, 22
	s_add_u32 s4, s0, 0x1e4cd900
	s_addc_u32 s5, s1, 0
	v_writelane_b32 v253, s4, 23
	v_mov_b32_e32 v248, 0xfcf
	v_mov_b32_e32 v249, 0xdf
	v_writelane_b32 v253, s5, 24
	s_add_u32 s4, s0, 0x1e4cda00
	s_addc_u32 s5, s1, 0
	v_writelane_b32 v253, s4, 25
	v_mov_b32_e32 v243, 0xfdf
	v_mov_b32_e32 v244, 0xef
	v_writelane_b32 v253, s5, 26
	s_add_u32 s4, s0, 0x1e4cdb00
	s_addc_u32 s5, s1, 0
	v_writelane_b32 v253, s4, 27
	v_mov_b32_e32 v245, 0xfef
	v_mov_b32_e32 v235, 0xff
	v_writelane_b32 v253, s5, 28
	s_add_u32 s4, s0, 0x1e4cdc00
	s_addc_u32 s5, s1, 0
	v_writelane_b32 v253, s4, 29
	v_mov_b32_e32 v246, 0xfff
	s_mov_b32 s34, 0x3fb8aa3b
	v_writelane_b32 v253, s5, 30
	s_add_u32 s4, s0, 0x1e4cdd00
	s_addc_u32 s5, s1, 0
	v_writelane_b32 v253, s4, 31
	s_mov_b32 s35, 0xc2ce8ed0
	s_mov_b32 s36, 0x42b17218
	v_writelane_b32 v253, s5, 32
	s_add_u32 s4, s0, 0x1e4cde00
	s_addc_u32 s5, s1, 0
	v_writelane_b32 v253, s4, 33
	s_mov_b32 s52, 0x800000
	s_movk_i32 s53, 0x1600
	v_writelane_b32 v253, s5, 34
	s_add_u32 s4, s0, 0x1e4cdf00
	s_addc_u32 s5, s1, 0
	v_writelane_b32 v253, s4, 35
	s_mov_b32 s85, 0
	s_mov_b64 s[92:93], -1
	v_writelane_b32 v253, s5, 36
	s_add_u32 s4, s0, 0x1e4ce000
	s_addc_u32 s5, s1, 0
	v_writelane_b32 v253, s4, 37
	s_mov_b32 s60, 0x3a800000
	s_mov_b64 s[96:97], 0x80
	v_writelane_b32 v253, s5, 38
	s_add_u32 s4, s0, 0x1e4ce100
	s_addc_u32 s5, s1, 0
	v_writelane_b32 v253, s4, 39
	s_nop 1
	v_writelane_b32 v253, s5, 40
	s_add_u32 s4, s0, 0x1e4ce200
	s_addc_u32 s5, s1, 0
	v_writelane_b32 v253, s4, 41
	s_nop 1
	v_writelane_b32 v253, s5, 42
	s_add_u32 s4, s0, 0x1e4ce300
	s_addc_u32 s5, s1, 0
	v_writelane_b32 v253, s4, 43
	s_cmp_eq_u32 s20, 15
	s_nop 0
	v_writelane_b32 v253, s5, 44
	s_cselect_b64 s[4:5], -1, 0
	v_writelane_b32 v253, s4, 45
	s_cmp_eq_u32 s20, 14
	s_nop 0
	v_writelane_b32 v253, s5, 46
	s_cselect_b64 s[4:5], -1, 0
	v_writelane_b32 v253, s4, 47
	s_cmp_eq_u32 s20, 13
	s_nop 0
	v_writelane_b32 v253, s5, 48
	s_cselect_b64 s[4:5], -1, 0
	v_writelane_b32 v253, s4, 49
	s_cmp_eq_u32 s20, 12
	s_nop 0
	v_writelane_b32 v253, s5, 50
	s_cselect_b64 s[4:5], -1, 0
	v_writelane_b32 v253, s4, 51
	s_cmp_eq_u32 s20, 11
	s_nop 0
	v_writelane_b32 v253, s5, 52
	s_cselect_b64 s[4:5], -1, 0
	v_writelane_b32 v253, s4, 53
	s_cmp_eq_u32 s20, 10
	s_nop 0
	v_writelane_b32 v253, s5, 54
	s_cselect_b64 s[4:5], -1, 0
	v_writelane_b32 v253, s4, 55
	s_cmp_eq_u32 s20, 9
	s_nop 0
	v_writelane_b32 v253, s5, 56
	s_cselect_b64 s[4:5], -1, 0
	v_writelane_b32 v253, s4, 57
	s_cmp_eq_u32 s20, 8
	s_nop 0
	v_writelane_b32 v253, s5, 58
	s_cselect_b64 s[4:5], -1, 0
	v_writelane_b32 v253, s4, 59
	s_cmp_eq_u32 s20, 7
	s_nop 0
	v_writelane_b32 v253, s5, 60
	s_cselect_b64 s[4:5], -1, 0
	v_writelane_b32 v253, s4, 61
	s_cmp_eq_u32 s20, 6
	s_nop 0
	v_writelane_b32 v253, s5, 62
	s_cselect_b64 s[4:5], -1, 0
	v_writelane_b32 v253, s4, 63
	s_cmp_eq_u32 s20, 5
	s_nop 0
	v_writelane_b32 v254, s5, 0
	s_cselect_b64 s[4:5], -1, 0
	v_writelane_b32 v254, s4, 1
	s_cmp_eq_u32 s20, 4
	s_nop 0
	v_writelane_b32 v254, s5, 2
	s_cselect_b64 s[4:5], -1, 0
	v_writelane_b32 v254, s4, 3
	s_cmp_eq_u32 s20, 3
	s_nop 0
	v_writelane_b32 v254, s5, 4
	s_cselect_b64 s[4:5], -1, 0
	v_writelane_b32 v254, s4, 5
	s_cmp_eq_u32 s20, 2
	s_nop 0
	v_writelane_b32 v254, s5, 6
	s_cselect_b64 s[4:5], -1, 0
	v_writelane_b32 v254, s4, 7
	s_cmp_eq_u32 s20, 1
	s_nop 0
	v_writelane_b32 v254, s5, 8
	s_cselect_b64 s[4:5], -1, 0
	v_writelane_b32 v254, s4, 9
	s_cmp_eq_u32 s20, 0
	s_nop 0
	v_writelane_b32 v254, s5, 10
	s_cselect_b64 s[4:5], -1, 0
	s_lshl_b32 s2, s20, 8
	v_writelane_b32 v254, s4, 11
	s_add_u32 s2, s8, s2
	s_movk_i32 s20, 0x400
	v_writelane_b32 v254, s5, 12
	s_addc_u32 s4, s9, 0
	s_add_u32 s6, s2, 0x1400
	s_addc_u32 s7, s4, 0
	v_writelane_b32 v254, s6, 13
	s_nop 1
	v_writelane_b32 v254, s7, 14
	s_add_u32 s6, s2, 0x2400
	s_addc_u32 s7, s4, 0
	v_writelane_b32 v254, s6, 15
	s_add_u32 s4, s0, 0x1e4d0400
	s_addc_u32 s5, s1, 0
	v_writelane_b32 v254, s7, 16
	v_writelane_b32 v254, s4, 17
	s_add_u32 s0, s0, 0x1e4d0500
	s_addc_u32 s1, s1, 0
	v_writelane_b32 v254, s5, 18
	v_writelane_b32 v254, s0, 19
	s_lshl_b32 s33, s54, 9
	s_mov_b32 s4, 0x3f803f80
	v_writelane_b32 v254, s1, 20
	s_lshl_b32 s0, s3, 9
	s_sub_i32 s0, s33, s0
	v_writelane_b32 v254, s0, 21
	s_lshl_b32 s0, s73, 6
	s_or_b32 s0, s0, 8
	v_writelane_b32 v254, s0, 22
	s_lshl_b32 s0, s73, 4
	v_writelane_b32 v254, s0, 23
	s_lshl_b32 s0, s54, 4
	v_writelane_b32 v254, s0, 24
	s_lshl_b32 s0, s54, 6
	v_writelane_b32 v254, s0, 25
	s_lshl_b32 s0, s73, 5
	v_writelane_b32 v254, s0, 26
	s_lshl_b32 s0, s54, 5
	v_writelane_b32 v254, s0, 27
	s_lshl_b32 s0, s73, 9
	v_writelane_b32 v254, s0, 28
	v_writelane_b32 v254, s4, 29
	s_mov_b32 s2, s54
	s_mov_b32 s0, 0
	v_writelane_b32 v254, s5, 30
	v_writelane_b32 v254, s6, 31
	v_writelane_b32 v254, s7, 32
	v_writelane_b32 v254, s73, 33
	v_writelane_b32 v254, s2, 34
	s_nop 1
	v_writelane_b32 v254, s3, 35
	v_writelane_b32 v254, s79, 36
	v_writelane_b32 v254, s55, 37
	v_writelane_b32 v254, s51, 38
	v_writelane_b32 v254, s33, 39
	v_writelane_b32 v254, s88, 40
	s_nop 1
	v_writelane_b32 v254, s89, 41
	v_writelane_b32 v254, s91, 42
	v_writelane_b32 v254, s18, 43
	s_nop 1
	v_writelane_b32 v254, s19, 44
	s_branch .LBB0_36

; DEV void ph_attn(const P& p, int l, bool need, char* smem) {
;     ...
;     attn_item(p, bh, qb * 256, 68, (bh >> 3) * 4096 + qb * 256, smem);
;   }
;   if (need) for (int it = blockIdx.x; it < 64; it += gridDim.x) attn_item(p, it, 4096, 4, MLAT + (it >> 3) * 256, smem);
.LBB0_223:
	v_readlane_b32 s2, v254, 54
	v_readlane_b32 s3, v254, 55
	s_andn2_b64 vcc, exec, s[2:3]
	s_cbranch_vccnz .LBB0_301
	s_add_u32 s12, s0, 0x15ccd000
	s_addc_u32 s13, s1, 0
	s_add_u32 s14, s0, 0x18fcd000
	s_addc_u32 s15, s1, 0
	s_add_u32 s16, s0, 0x1c2cd000
	s_addc_u32 s17, s1, 0
	s_cmpk_ge_i32 s54, 0x80
	s_cselect_b32 s18, 64, 0
	s_sub_i32 s18, s73, s18
	s_branch .LBB0_228
